# NSA selected loop: 32 rel-pos LUT LDS lookups per key tile hoisted and issued in 4 batches instead of 32 serialized round trips
# speedup vs baseline: 1.0034x; 1.0034x over previous
; template <int MODE>
; DI void attn_run(const bfu* __restrict__ Qp, const bfu* __restrict__ Kp, const bfu* __restrict__ Vtp, int qt,
;                  f32x16 (&o)[2], const float* __restrict__ cump, unsigned sel, unsigned blockmask, char* smem) {
;     ...
;         if (need_mask) {
; #pragma unroll
;           for (int mt = 0; mt < 2; ++mt)
; #pragma unroll
;             for (int i = 0; i < 16; ++i) {
;               const int kl = 32 * mt + (i & 3) + 8 * (i >> 2) + 4 * hh;
;               const int key = k0 + kl;
;               float s = sc[mt][i];
;               bool valid;
;               if (MODE == 1) valid = key <= t;
;               else if (MODE == 2) { valid = key <= t; s += cumq - cumk[kl]; }
;               else {
;                 int dd = t - key;
;                 if (MODE == 3) valid = (dd >= 0) && ((sel >> kt) & 1u); else valid = (dd >= 0) && (dd < 512);
;                 int di = dd < 0 ? 0 : (dd > 128 ? 128 : dd);
;                 s += lut[di];
;               }
.LBB0_464:
	s_lshl_b32 s2, s4, 6
	v_add_u32_e32 v32, s2, v110
	v_ashrrev_i32_e32 v33, 31, v32
	v_add_u32_e32 v34, s2, v111
	v_lshlrev_b64 v[32:33], 7, v[32:33]
	v_ashrrev_i32_e32 v35, 31, v34
	v_lshl_add_u64 v[32:33], v[100:101], 0, v[32:33]
	v_lshlrev_b64 v[34:35], 7, v[34:35]
	s_lshl_b32 s96, s4, 7
	v_lshl_add_u64 v[34:35], v[102:103], 0, v[34:35]
	global_load_dwordx4 v[84:87], v[32:33], off
	global_load_dwordx4 v[80:83], v[34:35], off
	v_lshl_add_u64 v[32:33], v[98:99], 0, s[96:97]
	v_lshl_add_u64 v[34:35], v[32:33], 0, v[104:105]
	v_lshl_add_u64 v[32:33], v[32:33], 0, v[106:107]
	global_load_dwordx4 v[92:95], v[34:35], off
	global_load_dwordx4 v[88:91], v[32:33], off
	s_lshl_b32 s2, s33, 6
	v_cmp_le_i32_e32 vcc, s2, v97
	s_and_saveexec_b64 s[8:9], vcc
	s_cbranch_execz .LBB0_468
	ds_read_b128 v[32:35], v132
	ds_read_b128 v[36:39], v132 offset:32
	v_subrev_u32_e32 v150, s2, v96
	v_sub_u32_e32 v153, v150, v112
	v_med3_i32 v153, v153, 0, v230
	v_lshlrev_b32_e32 v153, 2, v153
	ds_read_b32 v153, v153 offset:22816
	v_add_u32_e32 v154, v150, v113
	v_med3_i32 v154, v154, 0, v230
	v_lshlrev_b32_e32 v154, 2, v154
	ds_read_b32 v154, v154 offset:22816
	v_sub_u32_e32 v155, v150, v114
	v_med3_i32 v155, v155, 0, v230
	v_lshlrev_b32_e32 v155, 2, v155
	ds_read_b32 v155, v155 offset:22816
	v_sub_u32_e32 v156, v150, v115
	v_med3_i32 v156, v156, 0, v230
	v_lshlrev_b32_e32 v156, 2, v156
	ds_read_b32 v156, v156 offset:22816
	v_sub_u32_e32 v157, v150, v116
	v_med3_i32 v157, v157, 0, v230
	v_lshlrev_b32_e32 v157, 2, v157
	ds_read_b32 v157, v157 offset:22816
	v_sub_u32_e32 v158, v150, v117
	v_med3_i32 v158, v158, 0, v230
	v_lshlrev_b32_e32 v158, 2, v158
	ds_read_b32 v158, v158 offset:22816
	v_sub_u32_e32 v159, v150, v118
	v_med3_i32 v159, v159, 0, v230
	v_lshlrev_b32_e32 v159, 2, v159
	ds_read_b32 v159, v159 offset:22816
	v_sub_u32_e32 v163, v150, v119
	v_med3_i32 v163, v163, 0, v230
	v_lshlrev_b32_e32 v163, 2, v163
	ds_read_b32 v163, v163 offset:22816
	s_waitcnt lgkmcnt(4)
	v_sub_u32_e32 v164, v150, v120
	v_med3_i32 v164, v164, 0, v230
	v_lshlrev_b32_e32 v164, 2, v164
	ds_read_b32 v164, v164 offset:22816
	v_sub_u32_e32 v165, v150, v121
	v_med3_i32 v165, v165, 0, v230
	v_lshlrev_b32_e32 v165, 2, v165
	ds_read_b32 v165, v165 offset:22816
	v_sub_u32_e32 v166, v150, v122
	v_med3_i32 v166, v166, 0, v230
	v_lshlrev_b32_e32 v166, 2, v166
	ds_read_b32 v166, v166 offset:22816
	v_sub_u32_e32 v167, v150, v123
	v_med3_i32 v167, v167, 0, v230
	v_lshlrev_b32_e32 v167, 2, v167
	ds_read_b32 v167, v167 offset:22816
	v_sub_u32_e32 v168, v150, v124
	v_med3_i32 v168, v168, 0, v230
	v_lshlrev_b32_e32 v168, 2, v168
	ds_read_b32 v168, v168 offset:22816
	v_sub_u32_e32 v169, v150, v125
	v_med3_i32 v169, v169, 0, v230
	v_lshlrev_b32_e32 v169, 2, v169
	ds_read_b32 v169, v169 offset:22816
	v_sub_u32_e32 v170, v150, v126
	v_med3_i32 v170, v170, 0, v230
	v_lshlrev_b32_e32 v170, 2, v170
	ds_read_b32 v170, v170 offset:22816
	v_sub_u32_e32 v171, v150, v127
	v_med3_i32 v171, v171, 0, v230
	v_lshlrev_b32_e32 v171, 2, v171
	ds_read_b32 v171, v171 offset:22816
	s_waitcnt lgkmcnt(4)
	v_sub_u32_e32 v172, v150, v112
	v_add_u32_e32 v172, 0xffffffe0, v172
	v_med3_i32 v172, v172, 0, v230
	v_lshlrev_b32_e32 v172, 2, v172
	ds_read_b32 v172, v172 offset:22816
	v_add_u32_e32 v173, v150, v113
	v_add_u32_e32 v173, 0xffffffe0, v173
	v_med3_i32 v173, v173, 0, v230
	v_lshlrev_b32_e32 v173, 2, v173
	ds_read_b32 v173, v173 offset:22816
	v_sub_u32_e32 v174, v150, v114
	v_add_u32_e32 v174, 0xffffffe0, v174
	v_med3_i32 v174, v174, 0, v230
	v_lshlrev_b32_e32 v174, 2, v174
	ds_read_b32 v174, v174 offset:22816
	v_sub_u32_e32 v175, v150, v115
	v_add_u32_e32 v175, 0xffffffe0, v175
	v_med3_i32 v175, v175, 0, v230
	v_lshlrev_b32_e32 v175, 2, v175
	ds_read_b32 v175, v175 offset:22816
	v_sub_u32_e32 v176, v150, v116
	v_add_u32_e32 v176, 0xffffffe0, v176
	v_med3_i32 v176, v176, 0, v230
	v_lshlrev_b32_e32 v176, 2, v176
	ds_read_b32 v176, v176 offset:22816
	v_sub_u32_e32 v177, v150, v117
	v_add_u32_e32 v177, 0xffffffe0, v177
	v_med3_i32 v177, v177, 0, v230
	v_lshlrev_b32_e32 v177, 2, v177
	ds_read_b32 v177, v177 offset:22816
	v_sub_u32_e32 v178, v150, v118
	v_add_u32_e32 v178, 0xffffffe0, v178
	v_med3_i32 v178, v178, 0, v230
	v_lshlrev_b32_e32 v178, 2, v178
	ds_read_b32 v178, v178 offset:22816
	v_sub_u32_e32 v179, v150, v119
	v_add_u32_e32 v179, 0xffffffe0, v179
	v_med3_i32 v179, v179, 0, v230
	v_lshlrev_b32_e32 v179, 2, v179
	ds_read_b32 v179, v179 offset:22816
	s_waitcnt lgkmcnt(4)
	v_sub_u32_e32 v180, v150, v120
	v_add_u32_e32 v180, 0xffffffe0, v180
	v_med3_i32 v180, v180, 0, v230
	v_lshlrev_b32_e32 v180, 2, v180
	ds_read_b32 v180, v180 offset:22816
	v_sub_u32_e32 v181, v150, v121
	v_add_u32_e32 v181, 0xffffffe0, v181
	v_med3_i32 v181, v181, 0, v230
	v_lshlrev_b32_e32 v181, 2, v181
	ds_read_b32 v181, v181 offset:22816
	v_sub_u32_e32 v182, v150, v122
	v_add_u32_e32 v182, 0xffffffe0, v182
	v_med3_i32 v182, v182, 0, v230
	v_lshlrev_b32_e32 v182, 2, v182
	ds_read_b32 v182, v182 offset:22816
	v_sub_u32_e32 v183, v150, v123
	v_add_u32_e32 v183, 0xffffffe0, v183
	v_med3_i32 v183, v183, 0, v230
	v_lshlrev_b32_e32 v183, 2, v183
	ds_read_b32 v183, v183 offset:22816
	v_sub_u32_e32 v184, v150, v124
	v_add_u32_e32 v184, 0xffffffe0, v184
	v_med3_i32 v184, v184, 0, v230
	v_lshlrev_b32_e32 v184, 2, v184
	ds_read_b32 v184, v184 offset:22816
	v_sub_u32_e32 v185, v150, v125
	v_add_u32_e32 v185, 0xffffffe0, v185
	v_med3_i32 v185, v185, 0, v230
	v_lshlrev_b32_e32 v185, 2, v185
	ds_read_b32 v185, v185 offset:22816
	v_sub_u32_e32 v186, v150, v126
	v_add_u32_e32 v186, 0xffffffe0, v186
	v_med3_i32 v186, v186, 0, v230
	v_lshlrev_b32_e32 v186, 2, v186
	ds_read_b32 v186, v186 offset:22816
	v_sub_u32_e32 v187, v150, v127
	v_add_u32_e32 v187, 0xffffffe0, v187
	v_med3_i32 v187, v187, 0, v230
	v_lshlrev_b32_e32 v187, 2, v187
	ds_read_b32 v187, v187 offset:22816
	s_lshl_b32 s2, 1, s33
	v_and_b32_e32 v135, s2, v109
	s_waitcnt lgkmcnt(1)
; #define MFMA(a, b, c) __builtin_amdgcn_mfma_f32_32x32x16_bf16((a), (b), (c), 0, 0, 0)
; template <int MODE>
; DI void attn_run(const bfu* __restrict__ Qp, const bfu* __restrict__ Kp, const bfu* __restrict__ Vtp, int qt,
;                  f32x16 (&o)[2], const float* __restrict__ cump, unsigned sel, unsigned blockmask, char* smem) {
;     ...
; #pragma unroll
;       for (int mt = 0; mt < 2; ++mt) {
; #pragma unroll
;         for (int i = 0; i < 16; ++i) sc[mt][i] = 0.f;
; #pragma unroll
;         for (int ks = 0; ks < NKS; ++ks) {
;           bf16x8 a = *(const bf16x8*)(Ks + (32 * mt + r) * KP + ks * 16 + hh * 8);
;           sc[mt] = MFMA(a, qf[ks], sc[mt]);
;         }
;       }
;     ...
;         if (need_mask) {
; #pragma unroll
;           for (int mt = 0; mt < 2; ++mt)
; #pragma unroll
;             for (int i = 0; i < 16; ++i) {
;               const int kl = 32 * mt + (i & 3) + 8 * (i >> 2) + 4 * hh;
;               const int key = k0 + kl;
;               float s = sc[mt][i];
;               bool valid;
;               if (MODE == 1) valid = key <= t;
;               else if (MODE == 2) { valid = key <= t; s += cumq - cumk[kl]; }
;               else {
;                 int dd = t - key;
;                 if (MODE == 3) valid = (dd >= 0) && ((sel >> kt) & 1u); else valid = (dd >= 0) && (dd < 512);
;                 int di = dd < 0 ? 0 : (dd > 128 ? 128 : dd);
;                 s += lut[di];
;               }
;               s = valid ? s : -INFINITY;
;               sc[mt][i] = s; mxv = fmaxf(mxv, s);
	v_mfma_f32_32x32x16_bf16 v[48:63], v[32:35], v[64:67], 0
	ds_read_b128 v[32:35], v132 offset:64
	ds_read_b128 v[136:139], v132 offset:4640
	v_cmp_ne_u32_e32 vcc, 0, v135
	v_sub_u32_e32 v135, v150, v112
	v_cmp_lt_i32_e64 s[2:3], -1, v135
	s_and_b64 s[2:3], s[2:3], vcc
	s_mov_b32 s4, 0xff800000
	s_waitcnt lgkmcnt(2)
	v_mfma_f32_32x32x16_bf16 v[48:63], v[36:39], v[68:71], v[48:63]
	s_waitcnt lgkmcnt(1)
	v_mfma_f32_32x32x16_bf16 v[48:63], v[32:35], v[72:75], v[48:63]
	ds_read_b128 v[32:35], v132 offset:96
	s_waitcnt lgkmcnt(0)
	v_mfma_f32_32x32x16_bf16 v[48:63], v[32:35], v[76:79], v[48:63]
	ds_read_b128 v[32:35], v132 offset:4608
	s_waitcnt lgkmcnt(0)
	v_mfma_f32_32x32x16_bf16 v[32:47], v[32:35], v[64:67], 0
	v_mfma_f32_32x32x16_bf16 v[32:47], v[136:139], v[68:71], v[32:47]
	ds_read_b128 v[136:139], v132 offset:4672
	s_waitcnt lgkmcnt(0)
	v_mfma_f32_32x32x16_bf16 v[32:47], v[136:139], v[72:75], v[32:47]
	ds_read_b128 v[136:139], v132 offset:4704
	s_waitcnt lgkmcnt(0)
	v_mfma_f32_32x32x16_bf16 v[32:47], v[136:139], v[76:79], v[32:47]
	v_mov_b32_e32 v136, v153
	v_subrev_u32_e32 v135, 32, v135
	s_waitcnt lgkmcnt(0)
	v_add_f32_e32 v48, v48, v136
	v_add_u32_e32 v136, v150, v113
	v_mov_b32_e32 v137, v154
	v_cndmask_b32_e64 v48, v228, v48, s[2:3]
	v_cmp_lt_i32_e64 s[2:3], -1, v136
	s_and_b64 s[2:3], s[2:3], vcc
	s_waitcnt lgkmcnt(0)
	v_add_f32_e32 v49, v49, v137
	v_sub_u32_e32 v137, v150, v114
	v_mov_b32_e32 v138, v155
	v_cndmask_b32_e64 v49, v228, v49, s[2:3]
	v_cmp_lt_i32_e64 s[2:3], -1, v137
	s_and_b64 s[2:3], s[2:3], vcc
	v_max3_f32 v139, v48, s4, v49
	s_waitcnt lgkmcnt(0)
	v_add_f32_e32 v50, v50, v138
	v_sub_u32_e32 v138, v150, v115
	v_mov_b32_e32 v140, v156
	v_cndmask_b32_e64 v50, v228, v50, s[2:3]
	v_cmp_lt_i32_e64 s[2:3], -1, v138
	s_and_b64 s[2:3], s[2:3], vcc
	s_waitcnt lgkmcnt(0)
	v_add_f32_e32 v51, v51, v140
	v_cndmask_b32_e64 v51, v228, v51, s[2:3]
	v_max3_f32 v141, v139, v50, v51
	v_sub_u32_e32 v139, v150, v116
	v_mov_b32_e32 v140, v157
	v_cmp_lt_i32_e64 s[2:3], -1, v139
	s_and_b64 s[2:3], s[2:3], vcc
	s_waitcnt lgkmcnt(0)
	v_add_f32_e32 v52, v52, v140
	v_sub_u32_e32 v140, v150, v117
	v_mov_b32_e32 v142, v158
	v_cndmask_b32_e64 v52, v228, v52, s[2:3]
	v_cmp_lt_i32_e64 s[2:3], -1, v140
	s_and_b64 s[2:3], s[2:3], vcc
	s_waitcnt lgkmcnt(0)
	v_add_f32_e32 v53, v53, v142
	v_cndmask_b32_e64 v53, v228, v53, s[2:3]
	v_max3_f32 v143, v141, v52, v53
	v_sub_u32_e32 v141, v150, v118
	v_mov_b32_e32 v142, v159
	v_cmp_lt_i32_e64 s[2:3], -1, v141
	s_and_b64 s[2:3], s[2:3], vcc
	s_waitcnt lgkmcnt(0)
	v_add_f32_e32 v54, v54, v142
	v_sub_u32_e32 v142, v150, v119
	v_mov_b32_e32 v144, v163
	v_cndmask_b32_e64 v54, v228, v54, s[2:3]
	v_cmp_lt_i32_e64 s[2:3], -1, v142
	s_and_b64 s[2:3], s[2:3], vcc
	s_waitcnt lgkmcnt(0)
	v_add_f32_e32 v55, v55, v144
	v_cndmask_b32_e64 v55, v228, v55, s[2:3]
	v_max3_f32 v145, v143, v54, v55
	v_sub_u32_e32 v143, v150, v120
	v_mov_b32_e32 v144, v164
	v_cmp_lt_i32_e64 s[2:3], -1, v143
	s_and_b64 s[2:3], s[2:3], vcc
	s_waitcnt lgkmcnt(0)
	v_add_f32_e32 v56, v56, v144
	v_sub_u32_e32 v144, v150, v121
	v_mov_b32_e32 v146, v165
	v_cndmask_b32_e64 v56, v228, v56, s[2:3]
	v_cmp_lt_i32_e64 s[2:3], -1, v144
	s_and_b64 s[2:3], s[2:3], vcc
	s_waitcnt lgkmcnt(0)
	v_add_f32_e32 v57, v57, v146
	v_cndmask_b32_e64 v57, v228, v57, s[2:3]
	v_max3_f32 v147, v145, v56, v57
	v_sub_u32_e32 v145, v150, v122
	v_mov_b32_e32 v146, v166
	v_cmp_lt_i32_e64 s[2:3], -1, v145
	s_and_b64 s[2:3], s[2:3], vcc
	s_waitcnt lgkmcnt(0)
	v_add_f32_e32 v58, v58, v146
	v_sub_u32_e32 v146, v150, v123
	v_mov_b32_e32 v148, v167
	v_cndmask_b32_e64 v58, v228, v58, s[2:3]
	v_cmp_lt_i32_e64 s[2:3], -1, v146
	s_and_b64 s[2:3], s[2:3], vcc
	s_waitcnt lgkmcnt(0)
	v_add_f32_e32 v59, v59, v148
	v_cndmask_b32_e64 v59, v228, v59, s[2:3]
	v_max3_f32 v149, v147, v58, v59
	v_sub_u32_e32 v147, v150, v124
	v_mov_b32_e32 v148, v168
	v_cmp_lt_i32_e64 s[2:3], -1, v147
	s_and_b64 s[2:3], s[2:3], vcc
	s_waitcnt lgkmcnt(0)
	v_add_f32_e32 v60, v60, v148
	v_sub_u32_e32 v148, v150, v125
	v_mov_b32_e32 v151, v169
	v_cndmask_b32_e64 v60, v228, v60, s[2:3]
	v_cmp_lt_i32_e64 s[2:3], -1, v148
	s_and_b64 s[2:3], s[2:3], vcc
	s_waitcnt lgkmcnt(0)
	v_add_f32_e32 v61, v61, v151
	v_cndmask_b32_e64 v61, v228, v61, s[2:3]
	v_max3_f32 v151, v149, v60, v61
	v_sub_u32_e32 v149, v150, v126
	v_mov_b32_e32 v152, v170
	v_sub_u32_e32 v150, v150, v127
	v_cmp_lt_i32_e64 s[2:3], -1, v149
	s_and_b64 s[2:3], s[2:3], vcc
	s_waitcnt lgkmcnt(0)
	v_add_f32_e32 v62, v62, v152
	v_mov_b32_e32 v152, v171
	v_cndmask_b32_e64 v62, v228, v62, s[2:3]
	v_cmp_lt_i32_e64 s[2:3], -1, v150
	s_and_b64 s[2:3], s[2:3], vcc
	s_waitcnt lgkmcnt(0)
	v_add_f32_e32 v63, v63, v152
	v_cndmask_b32_e64 v63, v228, v63, s[2:3]
	v_cmp_lt_i32_e64 s[2:3], -1, v135
	v_mov_b32_e32 v135, v172
	s_and_b64 s[2:3], s[2:3], vcc
	v_max3_f32 v151, v151, v62, v63
	s_waitcnt lgkmcnt(0)
; template <int MODE>
; DI void attn_run(const bfu* __restrict__ Qp, const bfu* __restrict__ Kp, const bfu* __restrict__ Vtp, int qt,
;                  f32x16 (&o)[2], const float* __restrict__ cump, unsigned sel, unsigned blockmask, char* smem) {
;     ...
;         if (need_mask) {
; #pragma unroll
;           for (int mt = 0; mt < 2; ++mt)
; #pragma unroll
;             for (int i = 0; i < 16; ++i) {
;               const int kl = 32 * mt + (i & 3) + 8 * (i >> 2) + 4 * hh;
;               const int key = k0 + kl;
;               float s = sc[mt][i];
;               bool valid;
;               if (MODE == 1) valid = key <= t;
;               else if (MODE == 2) { valid = key <= t; s += cumq - cumk[kl]; }
;               else {
;                 int dd = t - key;
;                 if (MODE == 3) valid = (dd >= 0) && ((sel >> kt) & 1u); else valid = (dd >= 0) && (dd < 512);
;                 int di = dd < 0 ? 0 : (dd > 128 ? 128 : dd);
;                 s += lut[di];
;               }
;               s = valid ? s : -INFINITY;
;               sc[mt][i] = s; mxv = fmaxf(mxv, s);
;             }
;         } else {
; #pragma unroll
;           for (int mt = 0; mt < 2; ++mt)
; #pragma unroll
;             for (int i = 0; i < 16; ++i) {
;               const int kl = 32 * mt + (i & 3) + 8 * (i >> 2) + 4 * hh;
;               float s = sc[mt][i];
;               if (MODE == 2) s += cumq - cumk[kl];
;               if (MODE == 4) { int dd = t - (k0 + kl); s += lut[dd > 128 ? 128 : dd]; }
;               sc[mt][i] = s; mxv = fmaxf(mxv, s);
;             }
;         }
;         mxv = fmaxf(mxv, __shfl_xor(mxv, 32));
;         const float m_new = fmaxf(m, mxv);
;         const float m_use = (m_new == -INFINITY) ? 0.f : m_new;
;         if (__any(m_new != m)) {
;           const float alpha = __expf(m - m_use);
;           l *= alpha;
; #pragma unroll
;           for (int dt = 0; dt < 2; ++dt)
; #pragma unroll
;             for (int i = 0; i < 16; ++i) o[dt][i] *= alpha;
;         }
	v_add_f32_e32 v32, v32, v135
	v_subrev_u32_e32 v135, 32, v136
	v_cndmask_b32_e64 v32, v228, v32, s[2:3]
	v_cmp_lt_i32_e64 s[2:3], -1, v135
	v_mov_b32_e32 v135, v173
	s_and_b64 s[2:3], s[2:3], vcc
	v_subrev_u32_e32 v136, 32, v137
	s_waitcnt lgkmcnt(0)
	v_add_f32_e32 v33, v33, v135
	v_cndmask_b32_e64 v135, v228, v33, s[2:3]
	v_cmp_lt_i32_e64 s[2:3], -1, v136
	v_mov_b32_e32 v136, v174
	s_and_b64 s[2:3], s[2:3], vcc
	v_max3_f32 v33, v151, v32, v135
	s_waitcnt lgkmcnt(0)
	v_add_f32_e32 v34, v34, v136
	v_subrev_u32_e32 v136, 32, v138
	v_cndmask_b32_e64 v34, v228, v34, s[2:3]
	v_cmp_lt_i32_e64 s[2:3], -1, v136
	v_mov_b32_e32 v136, v175
	s_and_b64 s[2:3], s[2:3], vcc
	s_waitcnt lgkmcnt(0)
	v_add_f32_e32 v35, v35, v136
	v_subrev_u32_e32 v136, 32, v139
	v_cndmask_b32_e64 v35, v228, v35, s[2:3]
	v_cmp_lt_i32_e64 s[2:3], -1, v136
	v_mov_b32_e32 v136, v176
	s_and_b64 s[2:3], s[2:3], vcc
	v_max3_f32 v33, v33, v34, v35
	s_waitcnt lgkmcnt(0)
	v_add_f32_e32 v36, v36, v136
	v_subrev_u32_e32 v136, 32, v140
	v_cndmask_b32_e64 v36, v228, v36, s[2:3]
	v_cmp_lt_i32_e64 s[2:3], -1, v136
	v_mov_b32_e32 v136, v177
	s_and_b64 s[2:3], s[2:3], vcc
	s_waitcnt lgkmcnt(0)
	v_add_f32_e32 v37, v37, v136
	v_subrev_u32_e32 v136, 32, v141
	v_cndmask_b32_e64 v37, v228, v37, s[2:3]
	v_cmp_lt_i32_e64 s[2:3], -1, v136
	v_mov_b32_e32 v136, v178
	s_and_b64 s[2:3], s[2:3], vcc
	v_max3_f32 v33, v33, v36, v37
	s_waitcnt lgkmcnt(0)
	v_add_f32_e32 v38, v38, v136
	v_subrev_u32_e32 v136, 32, v142
	v_cndmask_b32_e64 v38, v228, v38, s[2:3]
	v_cmp_lt_i32_e64 s[2:3], -1, v136
	v_mov_b32_e32 v136, v179
	s_and_b64 s[2:3], s[2:3], vcc
	s_waitcnt lgkmcnt(0)
	v_add_f32_e32 v39, v39, v136
	v_subrev_u32_e32 v136, 32, v143
	v_cndmask_b32_e64 v39, v228, v39, s[2:3]
	v_cmp_lt_i32_e64 s[2:3], -1, v136
	v_mov_b32_e32 v136, v180
	s_and_b64 s[2:3], s[2:3], vcc
	v_max3_f32 v33, v33, v38, v39
	s_waitcnt lgkmcnt(0)
	v_add_f32_e32 v40, v40, v136
	v_subrev_u32_e32 v136, 32, v144
	v_cndmask_b32_e64 v40, v228, v40, s[2:3]
	v_cmp_lt_i32_e64 s[2:3], -1, v136
	v_mov_b32_e32 v136, v181
	s_and_b64 s[2:3], s[2:3], vcc
	s_waitcnt lgkmcnt(0)
	v_add_f32_e32 v41, v41, v136
	v_subrev_u32_e32 v136, 32, v145
	v_cndmask_b32_e64 v41, v228, v41, s[2:3]
	v_cmp_lt_i32_e64 s[2:3], -1, v136
	v_mov_b32_e32 v136, v182
	s_and_b64 s[2:3], s[2:3], vcc
	v_max3_f32 v33, v33, v40, v41
	s_waitcnt lgkmcnt(0)
	v_add_f32_e32 v42, v42, v136
	v_cndmask_b32_e64 v136, v228, v42, s[2:3]
	v_subrev_u32_e32 v42, 32, v146
	v_cmp_lt_i32_e64 s[2:3], -1, v42
	v_mov_b32_e32 v42, v183
	s_and_b64 s[2:3], s[2:3], vcc
	s_waitcnt lgkmcnt(0)
	v_add_f32_e32 v42, v43, v42
	v_cndmask_b32_e64 v137, v228, v42, s[2:3]
	v_subrev_u32_e32 v42, 32, v147
	v_cmp_lt_i32_e64 s[2:3], -1, v42
	v_mov_b32_e32 v42, v184
	s_and_b64 s[2:3], s[2:3], vcc
	v_and_b32_e32 v43, 64, v227
	v_add_u32_e32 v43, 64, v43
	v_max3_f32 v33, v33, v136, v137
	s_waitcnt lgkmcnt(0)
	v_add_f32_e32 v42, v44, v42
	v_cndmask_b32_e64 v138, v228, v42, s[2:3]
	v_subrev_u32_e32 v42, 32, v148
	v_cmp_lt_i32_e64 s[2:3], -1, v42
	v_mov_b32_e32 v42, v185
	s_and_b64 s[2:3], s[2:3], vcc
	s_waitcnt lgkmcnt(0)
	v_add_f32_e32 v42, v45, v42
	v_cndmask_b32_e64 v139, v228, v42, s[2:3]
	v_subrev_u32_e32 v42, 32, v149
	v_cmp_lt_i32_e64 s[2:3], -1, v42
	v_mov_b32_e32 v42, v186
	s_and_b64 s[2:3], s[2:3], vcc
	v_max3_f32 v33, v33, v138, v139
	s_waitcnt lgkmcnt(0)
	v_add_f32_e32 v42, v46, v42
	v_cndmask_b32_e64 v140, v228, v42, s[2:3]
	v_subrev_u32_e32 v42, 32, v150
	v_cmp_lt_i32_e64 s[2:3], -1, v42
	v_mov_b32_e32 v42, v187
	s_and_b64 vcc, s[2:3], vcc
	s_waitcnt lgkmcnt(0)
	v_add_f32_e32 v42, v47, v42
	v_cndmask_b32_e32 v141, v228, v42, vcc
	v_xor_b32_e32 v42, 32, v227
	v_cmp_lt_i32_e32 vcc, v42, v43
	v_max3_f32 v33, v33, v140, v141
	s_nop 0
	v_cndmask_b32_e32 v42, v227, v42, vcc
	v_lshlrev_b32_e32 v42, 2, v42
	ds_bpermute_b32 v42, v42, v33
	s_waitcnt lgkmcnt(0)
	v_max3_f32 v33, v134, v33, v42
	v_cmp_neq_f32_e32 vcc, s4, v33
	s_nop 1
	v_cndmask_b32_e32 v42, 0, v33, vcc
	v_cmp_neq_f32_e32 vcc, v33, v134
	s_cbranch_vccz .LBB0_467
	v_sub_f32_e32 v43, v134, v42
	v_mul_f32_e32 v43, 0x3fb8aa3b, v43
	v_exp_f32_e32 v44, v43
	s_nop 0
	v_pk_mul_f32 v[14:15], v[14:15], v[44:45] op_sel_hi:[1,0]
	v_pk_mul_f32 v[12:13], v[12:13], v[44:45] op_sel_hi:[1,0]
	v_pk_mul_f32 v[10:11], v[10:11], v[44:45] op_sel_hi:[1,0]
	v_pk_mul_f32 v[8:9], v[8:9], v[44:45] op_sel_hi:[1,0]
	v_pk_mul_f32 v[6:7], v[6:7], v[44:45] op_sel_hi:[1,0]
	v_pk_mul_f32 v[4:5], v[4:5], v[44:45] op_sel_hi:[1,0]
	v_pk_mul_f32 v[2:3], v[2:3], v[44:45] op_sel_hi:[1,0]
	v_pk_mul_f32 v[0:1], v[0:1], v[44:45] op_sel_hi:[1,0]
	v_pk_mul_f32 v[30:31], v[30:31], v[44:45] op_sel_hi:[1,0]
	v_pk_mul_f32 v[28:29], v[28:29], v[44:45] op_sel_hi:[1,0]
	v_pk_mul_f32 v[26:27], v[26:27], v[44:45] op_sel_hi:[1,0]
	v_pk_mul_f32 v[24:25], v[24:25], v[44:45] op_sel_hi:[1,0]
	v_pk_mul_f32 v[22:23], v[22:23], v[44:45] op_sel_hi:[1,0]
	v_pk_mul_f32 v[20:21], v[20:21], v[44:45] op_sel_hi:[1,0]
	v_pk_mul_f32 v[18:19], v[18:19], v[44:45] op_sel_hi:[1,0]
	v_pk_mul_f32 v[16:17], v[16:17], v[44:45] op_sel_hi:[1,0]
	v_mul_f32_e32 v162, v162, v44
